# conv item: LayerNorm gain/bias loads issued before the stats barrier instead of after it (prologue/epilogue de-serialisation), on top of v17
# speedup vs baseline: 1.0028x; 1.0028x over previous
; __device__ __forceinline__ unsigned cvtpk(float lo, float hi) { f32x2_t v = {lo, hi}; bf16x2_t b = __builtin_convertvector(v, bf16x2_t); return __builtin_bit_cast(unsigned, b); }
; __device__ __forceinline__ float siluf_(float x) { return x * sigmoidf_(x); }
; __device__ __forceinline__ void conv_item(LAS unsigned char* lds, const bf16* PROJ, bf16* MIX, const float* cw, const float* cb, const float* lg, const float* lb, int item, int tid) {
;     ...
;     __syncthreads();
;     const float g = lg[c], bb = lb[c];
; #pragma unroll
;     for (int tk = 0; tk < 32; ++tk) { const float y = (acc[tk] - st[2 * tk]) * st[2 * tk + 1] * g + bb; const float ov = siluf_(y);
;         MIX[(size_t)(row0 + tk) * D + 512 + c] = (bf16)(cvtpk(ov, 0.f) & 0xffffu); }
.LBB0_440:
	s_or_b64 exec, exec, s[0:1]
	s_add_u32 s0, s20, s14
	s_addc_u32 s1, s21, s15
	s_add_u32 s4, s22, s14
	s_addc_u32 s5, s23, s15
	v_lshlrev_b64 v[4:5], 2, v[200:201]
	v_lshl_add_u64 v[6:7], s[0:1], 0, v[4:5]
	v_lshl_add_u64 v[4:5], s[4:5], 0, v[4:5]
	global_load_dword v8, v[6:7], off
	global_load_dword v0, v[4:5], off
	s_waitcnt lgkmcnt(0)
	s_barrier
	s_add_i32 s0, 0, 0x10000
	v_mov_b32_e32 v4, s0
	ds_read_b128 v[10:13], v4
	s_waitcnt lgkmcnt(0)
	v_sub_f32_e32 v4, v93, v10
	v_mul_f32_e32 v4, v4, v11
	s_waitcnt vmcnt(0)
	v_fma_f32 v4, v8, v4, v0
	v_mul_f32_e32 v5, 0xbfb8aa3b, v4
	v_exp_f32_e32 v5, v5
	s_nop 0
	v_add_f32_e32 v5, 1.0, v5
	v_rcp_f32_e32 v5, v5
	s_nop 0
	v_mul_f32_e32 v4, v4, v5
	v_cvt_pk_bf16_f32 v4, v4, s0
	s_lshl_b32 s0, s2, 16
	s_add_u32 s0, s90, s0
	s_addc_u32 s1, s91, 0
	v_lshl_add_u64 v[6:7], v[200:201], 1, s[0:1]
	global_store_short v[6:7], v4, off offset:1024
	v_sub_f32_e32 v4, v90, v12
	v_mul_f32_e32 v4, v4, v13
	v_fma_f32 v4, v8, v4, v0
	v_mul_f32_e32 v5, 0xbfb8aa3b, v4
	v_exp_f32_e32 v5, v5
	s_nop 0
	v_add_f32_e32 v5, 1.0, v5
	v_rcp_f32_e32 v5, v5
	s_nop 0
	v_mul_f32_e32 v4, v4, v5
	v_cvt_pk_bf16_f32 v4, v4, s0
	v_readlane_b32 s0, v254, 49
	global_store_short v[6:7], v4, off offset:3072
	s_nop 0
	v_mov_b32_e32 v4, s0
	ds_read_b128 v[10:13], v4
	s_waitcnt lgkmcnt(0)
	v_sub_f32_e32 v2, v2, v10
	v_mul_f32_e32 v2, v2, v11
	v_fma_f32 v2, v8, v2, v0
	v_mul_f32_e32 v4, 0xbfb8aa3b, v2
	v_exp_f32_e32 v4, v4
	s_nop 0
	v_add_f32_e32 v4, 1.0, v4
	v_rcp_f32_e32 v4, v4
	s_nop 0
	v_mul_f32_e32 v2, v2, v4
	v_cvt_pk_bf16_f32 v2, v2, s0
	s_movk_i32 s0, 0x1000
	v_add_co_u32_e32 v4, vcc, s0, v6
	s_nop 1
	v_addc_co_u32_e32 v5, vcc, 0, v7, vcc
	global_store_short v[4:5], v2, off offset:1024
	v_sub_f32_e32 v2, v86, v12
	v_mul_f32_e32 v2, v2, v13
	v_fma_f32 v2, v8, v2, v0
	v_mul_f32_e32 v9, 0xbfb8aa3b, v2
	v_exp_f32_e32 v9, v9
	s_nop 0
	v_add_f32_e32 v9, 1.0, v9
	v_rcp_f32_e32 v9, v9
	s_nop 0
	v_mul_f32_e32 v2, v2, v9
	v_cvt_pk_bf16_f32 v2, v2, s0
	v_readlane_b32 s0, v254, 50
	global_store_short v[4:5], v2, off offset:3072
	s_nop 0
	v_mov_b32_e32 v2, s0
	ds_read_b128 v[10:13], v2
	s_waitcnt lgkmcnt(0)
	v_sub_f32_e32 v2, v3, v10
	v_mul_f32_e32 v2, v2, v11
	v_fma_f32 v2, v8, v2, v0
	v_mul_f32_e32 v3, 0xbfb8aa3b, v2
	v_exp_f32_e32 v3, v3
	s_nop 0
	v_add_f32_e32 v3, 1.0, v3
	v_rcp_f32_e32 v3, v3
	s_nop 0
	v_mul_f32_e32 v2, v2, v3
	v_cvt_pk_bf16_f32 v4, v2, s0
	s_movk_i32 s0, 0x2000
	v_add_co_u32_e32 v2, vcc, s0, v6
	s_nop 1
	v_addc_co_u32_e32 v3, vcc, 0, v7, vcc
	global_store_short v[2:3], v4, off offset:1024
	v_sub_f32_e32 v4, v84, v12
	v_mul_f32_e32 v4, v4, v13
	v_fma_f32 v4, v8, v4, v0
	v_mul_f32_e32 v5, 0xbfb8aa3b, v4
	v_exp_f32_e32 v5, v5
	s_nop 0
	v_add_f32_e32 v5, 1.0, v5
	v_rcp_f32_e32 v5, v5
	s_nop 0
	v_mul_f32_e32 v4, v4, v5
	v_cvt_pk_bf16_f32 v4, v4, s0
	v_readlane_b32 s0, v254, 51
	global_store_short v[2:3], v4, off offset:3072
	s_nop 0
	v_mov_b32_e32 v2, s0
	ds_read_b128 v[2:5], v2
	s_waitcnt lgkmcnt(0)
	v_sub_f32_e32 v2, v83, v2
	v_mul_f32_e32 v2, v2, v3
	v_fma_f32 v2, v8, v2, v0
	v_sub_f32_e32 v4, v82, v4
	v_mul_f32_e32 v3, 0xbfb8aa3b, v2
	v_mul_f32_e32 v4, v4, v5
	v_exp_f32_e32 v3, v3
	v_fma_f32 v4, v8, v4, v0
	v_mul_f32_e32 v5, 0xbfb8aa3b, v4
	v_exp_f32_e32 v5, v5
	v_add_f32_e32 v3, 1.0, v3
	v_rcp_f32_e32 v3, v3
	v_add_f32_e32 v5, 1.0, v5
	v_rcp_f32_e32 v5, v5
	v_mul_f32_e32 v2, v2, v3
	v_cvt_pk_bf16_f32 v9, v2, s0
	s_movk_i32 s0, 0x3000
	v_add_co_u32_e32 v2, vcc, s0, v6
	v_mul_f32_e32 v4, v4, v5
	s_nop 0
	v_addc_co_u32_e32 v3, vcc, 0, v7, vcc
	v_cvt_pk_bf16_f32 v4, v4, s0
	v_readlane_b32 s0, v254, 52
	global_store_short v[2:3], v9, off offset:1024
	global_store_short v[2:3], v4, off offset:3072
	v_mov_b32_e32 v2, s0
	ds_read_b128 v[2:5], v2
	s_waitcnt lgkmcnt(0)
	v_sub_f32_e32 v2, v81, v2
	v_mul_f32_e32 v2, v2, v3
	v_fma_f32 v2, v8, v2, v0
	v_sub_f32_e32 v4, v80, v4
	v_mul_f32_e32 v3, 0xbfb8aa3b, v2
	v_mul_f32_e32 v4, v4, v5
	v_exp_f32_e32 v3, v3
	v_fma_f32 v4, v8, v4, v0
	v_mul_f32_e32 v5, 0xbfb8aa3b, v4
	v_exp_f32_e32 v5, v5
	v_add_f32_e32 v3, 1.0, v3
	v_rcp_f32_e32 v3, v3
	v_add_f32_e32 v5, 1.0, v5
	v_rcp_f32_e32 v5, v5
	v_mul_f32_e32 v2, v2, v3
	v_cvt_pk_bf16_f32 v9, v2, s0
	s_movk_i32 s0, 0x4000
	v_add_co_u32_e32 v2, vcc, s0, v6
	v_mul_f32_e32 v4, v4, v5
	s_nop 0
	v_addc_co_u32_e32 v3, vcc, 0, v7, vcc
	v_cvt_pk_bf16_f32 v4, v4, s0
	v_readlane_b32 s0, v254, 53
	global_store_short v[2:3], v9, off offset:1024
	global_store_short v[2:3], v4, off offset:3072
	v_mov_b32_e32 v2, s0
	ds_read_b128 v[2:5], v2
	s_waitcnt lgkmcnt(0)
	v_sub_f32_e32 v2, v79, v2
	v_mul_f32_e32 v2, v2, v3
	v_sub_f32_e32 v4, v78, v4
	v_fma_f32 v2, v8, v2, v0
	v_mul_f32_e32 v4, v4, v5
	v_mul_f32_e32 v3, 0xbfb8aa3b, v2
	v_fma_f32 v4, v8, v4, v0
	v_exp_f32_e32 v3, v3
	v_mul_f32_e32 v5, 0xbfb8aa3b, v4
	v_exp_f32_e32 v5, v5
	v_add_f32_e32 v3, 1.0, v3
	v_rcp_f32_e32 v3, v3
	v_add_f32_e32 v5, 1.0, v5
	v_rcp_f32_e32 v5, v5
	v_mul_f32_e32 v2, v2, v3
	v_cvt_pk_bf16_f32 v9, v2, s0
	v_add_co_u32_e32 v2, vcc, s35, v6
	v_mul_f32_e32 v4, v4, v5
	s_nop 0
	v_addc_co_u32_e32 v3, vcc, 0, v7, vcc
	v_cvt_pk_bf16_f32 v4, v4, s0
	v_readlane_b32 s0, v254, 54
	global_store_short v[2:3], v9, off offset:1024
	global_store_short v[2:3], v4, off offset:3072
	v_mov_b32_e32 v2, s0
	ds_read_b128 v[2:5], v2
	s_waitcnt lgkmcnt(0)
; __device__ __forceinline__ unsigned cvtpk(float lo, float hi) { f32x2_t v = {lo, hi}; bf16x2_t b = __builtin_convertvector(v, bf16x2_t); return __builtin_bit_cast(unsigned, b); }
; __device__ __forceinline__ float siluf_(float x) { return x * sigmoidf_(x); }
; __device__ __forceinline__ void conv_item(LAS unsigned char* lds, const bf16* PROJ, bf16* MIX, const float* cw, const float* cb, const float* lg, const float* lb, int item, int tid) {
;     ...
;     for (int tk = 0; tk < 32; ++tk) { const float y = (acc[tk] - st[2 * tk]) * st[2 * tk + 1] * g + bb; const float ov = siluf_(y);
;         MIX[(size_t)(row0 + tk) * D + 512 + c] = (bf16)(cvtpk(ov, 0.f) & 0xffffu); }
	v_sub_f32_e32 v2, v77, v2
	v_mul_f32_e32 v2, v2, v3
	v_fma_f32 v2, v8, v2, v0
	v_sub_f32_e32 v4, v70, v4
	v_mul_f32_e32 v3, 0xbfb8aa3b, v2
	v_mul_f32_e32 v4, v4, v5
	v_exp_f32_e32 v3, v3
	v_fma_f32 v4, v8, v4, v0
	v_mul_f32_e32 v5, 0xbfb8aa3b, v4
	v_exp_f32_e32 v5, v5
	v_add_f32_e32 v3, 1.0, v3
	v_rcp_f32_e32 v3, v3
	v_add_f32_e32 v5, 1.0, v5
	v_rcp_f32_e32 v5, v5
	v_mul_f32_e32 v2, v2, v3
	v_cvt_pk_bf16_f32 v9, v2, s0
	s_movk_i32 s0, 0x6000
	v_add_co_u32_e32 v2, vcc, s0, v6
	v_mul_f32_e32 v4, v4, v5
	s_nop 0
	v_addc_co_u32_e32 v3, vcc, 0, v7, vcc
	v_cvt_pk_bf16_f32 v4, v4, s0
	v_readlane_b32 s0, v254, 55
	global_store_short v[2:3], v9, off offset:1024
	global_store_short v[2:3], v4, off offset:3072
	v_mov_b32_e32 v2, s0
	ds_read_b128 v[2:5], v2
	s_waitcnt lgkmcnt(0)
	v_sub_f32_e32 v2, v69, v2
	v_mul_f32_e32 v2, v2, v3
	v_fma_f32 v2, v8, v2, v0
	v_sub_f32_e32 v4, v64, v4
	v_mul_f32_e32 v3, 0xbfb8aa3b, v2
	v_mul_f32_e32 v4, v4, v5
	v_exp_f32_e32 v3, v3
	v_fma_f32 v4, v8, v4, v0
	v_mul_f32_e32 v5, 0xbfb8aa3b, v4
	v_exp_f32_e32 v5, v5
	v_add_f32_e32 v3, 1.0, v3
	v_rcp_f32_e32 v3, v3
	v_add_f32_e32 v5, 1.0, v5
	v_rcp_f32_e32 v5, v5
	v_mul_f32_e32 v2, v2, v3
	v_cvt_pk_bf16_f32 v9, v2, s0
	s_movk_i32 s0, 0x7000
	v_add_co_u32_e32 v2, vcc, s0, v6
	v_mul_f32_e32 v4, v4, v5
	s_nop 0
	v_addc_co_u32_e32 v3, vcc, 0, v7, vcc
	v_cvt_pk_bf16_f32 v4, v4, s0
	v_readlane_b32 s0, v254, 56
	global_store_short v[2:3], v9, off offset:1024
	global_store_short v[2:3], v4, off offset:3072
	v_mov_b32_e32 v2, s0
	ds_read_b128 v[2:5], v2
	s_waitcnt lgkmcnt(0)
	v_sub_f32_e32 v2, v62, v2
	v_mul_f32_e32 v2, v2, v3
	v_sub_f32_e32 v4, v55, v4
	v_fma_f32 v2, v8, v2, v0
	v_mul_f32_e32 v4, v4, v5
	v_mul_f32_e32 v3, 0xbfb8aa3b, v2
	v_fma_f32 v4, v8, v4, v0
	v_exp_f32_e32 v3, v3
	v_mul_f32_e32 v5, 0xbfb8aa3b, v4
	v_exp_f32_e32 v5, v5
	v_add_f32_e32 v3, 1.0, v3
	v_rcp_f32_e32 v3, v3
	v_add_f32_e32 v5, 1.0, v5
	v_rcp_f32_e32 v5, v5
	v_mul_f32_e32 v2, v2, v3
	v_cvt_pk_bf16_f32 v9, v2, s0
	v_add_co_u32_e32 v2, vcc, s37, v6
	v_mul_f32_e32 v4, v4, v5
	s_nop 0
	v_addc_co_u32_e32 v3, vcc, 0, v7, vcc
	v_cvt_pk_bf16_f32 v4, v4, s0
	v_readlane_b32 s0, v254, 57
	global_store_short v[2:3], v9, off offset:1024
	global_store_short v[2:3], v4, off offset:3072
	v_mov_b32_e32 v2, s0
	ds_read_b128 v[2:5], v2
	s_waitcnt lgkmcnt(0)
	v_sub_f32_e32 v2, v54, v2
	v_mul_f32_e32 v2, v2, v3
	v_fma_f32 v2, v8, v2, v0
	v_sub_f32_e32 v4, v52, v4
	v_mul_f32_e32 v3, 0xbfb8aa3b, v2
	v_mul_f32_e32 v4, v4, v5
	v_exp_f32_e32 v3, v3
	v_fma_f32 v4, v8, v4, v0
	v_mul_f32_e32 v5, 0xbfb8aa3b, v4
	v_exp_f32_e32 v5, v5
	v_add_f32_e32 v3, 1.0, v3
	v_rcp_f32_e32 v3, v3
	v_add_f32_e32 v5, 1.0, v5
	v_rcp_f32_e32 v5, v5
	v_mul_f32_e32 v2, v2, v3
	v_cvt_pk_bf16_f32 v9, v2, s0
	s_mov_b32 s0, 0x9000
	v_add_co_u32_e32 v2, vcc, s0, v6
	v_mul_f32_e32 v4, v4, v5
	s_nop 0
	v_addc_co_u32_e32 v3, vcc, 0, v7, vcc
	v_cvt_pk_bf16_f32 v4, v4, s0
	v_readlane_b32 s0, v254, 58
	global_store_short v[2:3], v9, off offset:1024
	global_store_short v[2:3], v4, off offset:3072
	v_mov_b32_e32 v2, s0
	ds_read_b128 v[2:5], v2
	s_waitcnt lgkmcnt(0)
	v_sub_f32_e32 v2, v51, v2
	v_mul_f32_e32 v2, v2, v3
	v_sub_f32_e32 v4, v50, v4
	v_fma_f32 v2, v8, v2, v0
	v_mul_f32_e32 v4, v4, v5
	v_mul_f32_e32 v3, 0xbfb8aa3b, v2
	v_fma_f32 v4, v8, v4, v0
	v_exp_f32_e32 v3, v3
	v_mul_f32_e32 v5, 0xbfb8aa3b, v4
	v_exp_f32_e32 v5, v5
	v_add_f32_e32 v3, 1.0, v3
	v_rcp_f32_e32 v3, v3
	v_add_f32_e32 v5, 1.0, v5
	v_rcp_f32_e32 v5, v5
	v_mul_f32_e32 v2, v2, v3
	v_cvt_pk_bf16_f32 v9, v2, s0
	v_add_co_u32_e32 v2, vcc, s38, v6
	v_mul_f32_e32 v4, v4, v5
	s_nop 0
	v_addc_co_u32_e32 v3, vcc, 0, v7, vcc
	v_cvt_pk_bf16_f32 v4, v4, s0
	v_readlane_b32 s0, v254, 59
	global_store_short v[2:3], v9, off offset:1024
	global_store_short v[2:3], v4, off offset:3072
	v_mov_b32_e32 v2, s0
	ds_read_b128 v[2:5], v2
	s_waitcnt lgkmcnt(0)
; __device__ __forceinline__ unsigned cvtpk(float lo, float hi) { f32x2_t v = {lo, hi}; bf16x2_t b = __builtin_convertvector(v, bf16x2_t); return __builtin_bit_cast(unsigned, b); }
; __device__ __forceinline__ float siluf_(float x) { return x * sigmoidf_(x); }
; __device__ __forceinline__ void conv_item(LAS unsigned char* lds, const bf16* PROJ, bf16* MIX, const float* cw, const float* cb, const float* lg, const float* lb, int item, int tid) {
;     ...
;     for (int tk = 0; tk < 32; ++tk) { const float y = (acc[tk] - st[2 * tk]) * st[2 * tk + 1] * g + bb; const float ov = siluf_(y);
;         MIX[(size_t)(row0 + tk) * D + 512 + c] = (bf16)(cvtpk(ov, 0.f) & 0xffffu); }
;     __syncthreads();
	v_sub_f32_e32 v2, v49, v2
	v_mul_f32_e32 v2, v2, v3
	v_sub_f32_e32 v4, v46, v4
	v_fma_f32 v2, v8, v2, v0
	v_mul_f32_e32 v4, v4, v5
	v_mul_f32_e32 v3, 0xbfb8aa3b, v2
	v_fma_f32 v4, v8, v4, v0
	v_exp_f32_e32 v3, v3
	v_mul_f32_e32 v5, 0xbfb8aa3b, v4
	v_exp_f32_e32 v5, v5
	v_add_f32_e32 v3, 1.0, v3
	v_rcp_f32_e32 v3, v3
	v_add_f32_e32 v5, 1.0, v5
	v_rcp_f32_e32 v5, v5
	v_mul_f32_e32 v2, v2, v3
	v_cvt_pk_bf16_f32 v9, v2, s0
	v_add_co_u32_e32 v2, vcc, s51, v6
	v_mul_f32_e32 v4, v4, v5
	s_nop 0
	v_addc_co_u32_e32 v3, vcc, 0, v7, vcc
	v_cvt_pk_bf16_f32 v4, v4, s0
	v_readlane_b32 s0, v254, 60
	global_store_short v[2:3], v9, off offset:1024
	global_store_short v[2:3], v4, off offset:3072
	v_mov_b32_e32 v2, s0
	ds_read_b128 v[2:5], v2
	s_waitcnt lgkmcnt(0)
	v_sub_f32_e32 v2, v45, v2
	v_mul_f32_e32 v2, v2, v3
	v_sub_f32_e32 v4, v44, v4
	v_fma_f32 v2, v8, v2, v0
	v_mul_f32_e32 v4, v4, v5
	v_mul_f32_e32 v3, 0xbfb8aa3b, v2
	v_fma_f32 v4, v8, v4, v0
	v_exp_f32_e32 v3, v3
	v_mul_f32_e32 v5, 0xbfb8aa3b, v4
	v_exp_f32_e32 v5, v5
	v_add_f32_e32 v3, 1.0, v3
	v_rcp_f32_e32 v3, v3
	v_add_f32_e32 v5, 1.0, v5
	v_rcp_f32_e32 v5, v5
	v_mul_f32_e32 v2, v2, v3
	v_cvt_pk_bf16_f32 v9, v2, s0
	v_add_co_u32_e32 v2, vcc, s39, v6
	v_mul_f32_e32 v4, v4, v5
	s_nop 0
	v_addc_co_u32_e32 v3, vcc, 0, v7, vcc
	v_cvt_pk_bf16_f32 v4, v4, s0
	v_readlane_b32 s0, v254, 61
	global_store_short v[2:3], v9, off offset:1024
	global_store_short v[2:3], v4, off offset:3072
	v_mov_b32_e32 v2, s0
	ds_read_b128 v[2:5], v2
	s_waitcnt lgkmcnt(0)
	v_sub_f32_e32 v2, v43, v2
	v_mul_f32_e32 v2, v2, v3
	v_fma_f32 v2, v8, v2, v0
	v_sub_f32_e32 v4, v40, v4
	v_mul_f32_e32 v3, 0xbfb8aa3b, v2
	v_mul_f32_e32 v4, v4, v5
	v_exp_f32_e32 v3, v3
	v_fma_f32 v4, v8, v4, v0
	v_mul_f32_e32 v5, 0xbfb8aa3b, v4
	v_exp_f32_e32 v5, v5
	v_add_f32_e32 v3, 1.0, v3
	v_rcp_f32_e32 v3, v3
	v_add_f32_e32 v5, 1.0, v5
	v_rcp_f32_e32 v5, v5
	v_mul_f32_e32 v2, v2, v3
	v_cvt_pk_bf16_f32 v9, v2, s0
	s_mov_b32 s0, 0xd000
	v_add_co_u32_e32 v2, vcc, s0, v6
	v_mul_f32_e32 v4, v4, v5
	s_nop 0
	v_addc_co_u32_e32 v3, vcc, 0, v7, vcc
	v_cvt_pk_bf16_f32 v4, v4, s0
	v_readlane_b32 s0, v254, 62
	global_store_short v[2:3], v9, off offset:1024
	global_store_short v[2:3], v4, off offset:3072
	v_mov_b32_e32 v2, s0
	ds_read_b128 v[2:5], v2
	s_waitcnt lgkmcnt(0)
	v_sub_f32_e32 v2, v41, v2
	v_mul_f32_e32 v2, v2, v3
	v_sub_f32_e32 v4, v38, v4
	v_fma_f32 v2, v8, v2, v0
	v_mul_f32_e32 v4, v4, v5
	v_mul_f32_e32 v3, 0xbfb8aa3b, v2
	v_fma_f32 v4, v8, v4, v0
	v_exp_f32_e32 v3, v3
	v_mul_f32_e32 v5, 0xbfb8aa3b, v4
	v_exp_f32_e32 v5, v5
	v_add_f32_e32 v3, 1.0, v3
	v_rcp_f32_e32 v3, v3
	v_add_f32_e32 v5, 1.0, v5
	v_rcp_f32_e32 v5, v5
	v_mul_f32_e32 v2, v2, v3
	v_cvt_pk_bf16_f32 v9, v2, s0
	v_add_co_u32_e32 v2, vcc, s42, v6
	v_mul_f32_e32 v4, v4, v5
	s_nop 0
	v_addc_co_u32_e32 v3, vcc, 0, v7, vcc
	v_cvt_pk_bf16_f32 v4, v4, s0
	v_readlane_b32 s0, v254, 63
	global_store_short v[2:3], v9, off offset:1024
	global_store_short v[2:3], v4, off offset:3072
	v_mov_b32_e32 v2, s0
	ds_read_b128 v[2:5], v2
	s_waitcnt lgkmcnt(0)
	v_sub_f32_e32 v2, v37, v2
	v_mul_f32_e32 v2, v2, v3
	v_sub_f32_e32 v4, v34, v4
	v_fma_f32 v2, v8, v2, v0
	v_mul_f32_e32 v4, v4, v5
	v_mul_f32_e32 v3, 0xbfb8aa3b, v2
	v_fmac_f32_e32 v0, v8, v4
	v_exp_f32_e32 v3, v3
	v_mul_f32_e32 v4, 0xbfb8aa3b, v0
	v_exp_f32_e32 v4, v4
	v_add_f32_e32 v3, 1.0, v3
	v_rcp_f32_e32 v3, v3
	v_add_f32_e32 v4, 1.0, v4
	v_rcp_f32_e32 v4, v4
	v_mul_f32_e32 v2, v2, v3
	v_cvt_pk_bf16_f32 v9, v2, s0
	v_add_co_u32_e32 v2, vcc, s44, v6
	v_mul_f32_e32 v0, v0, v4
	s_nop 0
	v_addc_co_u32_e32 v3, vcc, 0, v7, vcc
	v_cvt_pk_bf16_f32 v0, v0, s0
	global_store_short v[2:3], v9, off offset:1024
	global_store_short v[2:3], v0, off offset:3072
	s_barrier
	s_mov_b64 s[0:1], 0
